# norm2_dyn: B-row bf16 loads issued together + async prefetch with deferred bf16->f32 conversion; norm A loop-top store drain removed; S0 silu table loads batched; SSD flag prefetch moved
# speedup vs baseline: 1.0069x; 1.0069x over previous
.LBB0_15:
	v_mov_b32_e32 v4, v6
	v_lshl_add_u64 v[8:9], s[6:7], 0, v[4:5]
	s_mov_b64 s[10:11], 0x1000
	v_lshl_add_u64 v[14:15], v[2:3], 0, s[10:11]
	v_lshl_add_u64 v[16:17], v[14:15], 0, s[10:11]
	v_lshl_add_u64 v[18:19], v[16:17], 0, s[10:11]
	global_load_dword v20, v[2:3], off
	global_load_dword v21, v[2:3], off offset:2048
	global_load_dword v22, v[14:15], off
	global_load_dword v23, v[14:15], off offset:2048
	global_load_dword v24, v[16:17], off
	global_load_dword v25, v[16:17], off offset:2048
	global_load_dword v26, v[18:19], off
	global_load_dword v27, v[18:19], off offset:2048
	global_load_dword v28, v[8:9], off
	global_load_dword v29, v[8:9], off offset:2048
	s_waitcnt vmcnt(9)
	v_mul_f32_e32 v8, 0xbfb8aa3b, v20
	v_exp_f32_e32 v8, v8
	s_nop 0
	v_add_f32_e32 v8, 1.0, v8
	v_div_scale_f32 v9, s[16:17], v8, v8, v20
	v_rcp_f32_e32 v10, v9
	v_div_scale_f32 v11, vcc, v20, v8, v20
	v_fma_f32 v12, -v9, v10, 1.0
	v_fmac_f32_e32 v10, v12, v10
	v_mul_f32_e32 v12, v11, v10
	v_fma_f32 v13, -v9, v12, v11
	v_fmac_f32_e32 v12, v13, v10
	v_fma_f32 v9, -v9, v12, v11
	v_div_fmas_f32 v9, v9, v10, v12
	v_div_fixup_f32 v4, v9, v8, v20
	ds_write_b32 v7, v4
	s_waitcnt vmcnt(8)
	v_mul_f32_e32 v8, 0xbfb8aa3b, v21
	v_exp_f32_e32 v8, v8
	s_nop 0
	v_add_f32_e32 v8, 1.0, v8
	v_div_scale_f32 v9, s[16:17], v8, v8, v21
	v_rcp_f32_e32 v10, v9
	v_div_scale_f32 v11, vcc, v21, v8, v21
	v_fma_f32 v12, -v9, v10, 1.0
	v_fmac_f32_e32 v10, v12, v10
	v_mul_f32_e32 v12, v11, v10
	v_fma_f32 v13, -v9, v12, v11
	v_fmac_f32_e32 v12, v13, v10
	v_fma_f32 v9, -v9, v12, v11
	v_div_fmas_f32 v9, v9, v10, v12
	v_div_fixup_f32 v4, v9, v8, v21
	ds_write_b32 v7, v4 offset:2048
	s_waitcnt vmcnt(7)
	v_mul_f32_e32 v8, 0xbfb8aa3b, v22
	v_exp_f32_e32 v8, v8
	s_nop 0
	v_add_f32_e32 v8, 1.0, v8
	v_div_scale_f32 v9, s[16:17], v8, v8, v22
	v_rcp_f32_e32 v10, v9
	v_div_scale_f32 v11, vcc, v22, v8, v22
	v_fma_f32 v12, -v9, v10, 1.0
	v_fmac_f32_e32 v10, v12, v10
	v_mul_f32_e32 v12, v11, v10
	v_fma_f32 v13, -v9, v12, v11
	v_fmac_f32_e32 v12, v13, v10
	v_fma_f32 v9, -v9, v12, v11
	v_div_fmas_f32 v9, v9, v10, v12
	v_div_fixup_f32 v4, v9, v8, v22
	ds_write_b32 v7, v4 offset:4096
	s_waitcnt vmcnt(6)
	v_mul_f32_e32 v8, 0xbfb8aa3b, v23
	v_exp_f32_e32 v8, v8
	s_nop 0
	v_add_f32_e32 v8, 1.0, v8
	v_div_scale_f32 v9, s[16:17], v8, v8, v23
	v_rcp_f32_e32 v10, v9
	v_div_scale_f32 v11, vcc, v23, v8, v23
	v_fma_f32 v12, -v9, v10, 1.0
	v_fmac_f32_e32 v10, v12, v10
	v_mul_f32_e32 v12, v11, v10
	v_fma_f32 v13, -v9, v12, v11
	v_fmac_f32_e32 v12, v13, v10
	v_fma_f32 v9, -v9, v12, v11
	v_div_fmas_f32 v9, v9, v10, v12
	v_div_fixup_f32 v4, v9, v8, v23
	ds_write_b32 v7, v4 offset:6144
	s_waitcnt vmcnt(5)
	v_mul_f32_e32 v8, 0xbfb8aa3b, v24
	v_exp_f32_e32 v8, v8
	s_nop 0
	v_add_f32_e32 v8, 1.0, v8
	v_div_scale_f32 v9, s[16:17], v8, v8, v24
	v_rcp_f32_e32 v10, v9
	v_div_scale_f32 v11, vcc, v24, v8, v24
	v_fma_f32 v12, -v9, v10, 1.0
	v_fmac_f32_e32 v10, v12, v10
	v_mul_f32_e32 v12, v11, v10
	v_fma_f32 v13, -v9, v12, v11
	v_fmac_f32_e32 v12, v13, v10
	v_fma_f32 v9, -v9, v12, v11
	v_div_fmas_f32 v9, v9, v10, v12
	v_div_fixup_f32 v4, v9, v8, v24
	ds_write_b32 v7, v4 offset:8192
	s_waitcnt vmcnt(4)
	v_mul_f32_e32 v8, 0xbfb8aa3b, v25
	v_exp_f32_e32 v8, v8
	s_nop 0
	v_add_f32_e32 v8, 1.0, v8
	v_div_scale_f32 v9, s[16:17], v8, v8, v25
	v_rcp_f32_e32 v10, v9
	v_div_scale_f32 v11, vcc, v25, v8, v25
	v_fma_f32 v12, -v9, v10, 1.0
	v_fmac_f32_e32 v10, v12, v10
	v_mul_f32_e32 v12, v11, v10
	v_fma_f32 v13, -v9, v12, v11
	v_fmac_f32_e32 v12, v13, v10
	v_fma_f32 v9, -v9, v12, v11
	v_div_fmas_f32 v9, v9, v10, v12
	v_div_fixup_f32 v4, v9, v8, v25
	ds_write_b32 v7, v4 offset:10240
	s_waitcnt vmcnt(3)
	v_mul_f32_e32 v8, 0xbfb8aa3b, v26
	v_exp_f32_e32 v8, v8
	s_nop 0
	v_add_f32_e32 v8, 1.0, v8
	v_div_scale_f32 v9, s[16:17], v8, v8, v26
	v_rcp_f32_e32 v10, v9
	v_div_scale_f32 v11, vcc, v26, v8, v26
	v_fma_f32 v12, -v9, v10, 1.0
	v_fmac_f32_e32 v10, v12, v10
	v_mul_f32_e32 v12, v11, v10
	v_fma_f32 v13, -v9, v12, v11
	v_fmac_f32_e32 v12, v13, v10
	v_fma_f32 v9, -v9, v12, v11
	v_div_fmas_f32 v9, v9, v10, v12
	v_div_fixup_f32 v4, v9, v8, v26
	ds_write_b32 v7, v4 offset:12288
	s_waitcnt vmcnt(2)
	v_mul_f32_e32 v8, 0xbfb8aa3b, v27
	v_exp_f32_e32 v8, v8
	s_nop 0
	v_add_f32_e32 v8, 1.0, v8
	v_div_scale_f32 v9, s[16:17], v8, v8, v27
	v_rcp_f32_e32 v10, v9
	v_div_scale_f32 v11, vcc, v27, v8, v27
	v_fma_f32 v12, -v9, v10, 1.0
	v_fmac_f32_e32 v10, v12, v10
	v_mul_f32_e32 v12, v11, v10
	v_fma_f32 v13, -v9, v12, v11
	v_fmac_f32_e32 v12, v13, v10
	v_fma_f32 v9, -v9, v12, v11
	v_div_fmas_f32 v9, v9, v10, v12
	v_div_fixup_f32 v4, v9, v8, v27
	ds_write_b32 v7, v4 offset:14336
	s_waitcnt vmcnt(1)
	v_mul_f32_e32 v8, 0xbfb8aa3b, v28
	v_exp_f32_e32 v8, v8
	s_nop 0
	v_add_f32_e32 v8, 1.0, v8
	v_div_scale_f32 v9, s[16:17], v8, v8, v28
	v_rcp_f32_e32 v10, v9
	v_div_scale_f32 v11, vcc, v28, v8, v28
	v_fma_f32 v12, -v9, v10, 1.0
	v_fmac_f32_e32 v10, v12, v10
	v_mul_f32_e32 v12, v11, v10
	v_fma_f32 v13, -v9, v12, v11
	v_fmac_f32_e32 v12, v13, v10
	v_fma_f32 v9, -v9, v12, v11
	v_div_fmas_f32 v9, v9, v10, v12
	v_div_fixup_f32 v4, v9, v8, v28
	ds_write_b32 v7, v4 offset:16384
	s_waitcnt vmcnt(0)
	v_mul_f32_e32 v8, 0xbfb8aa3b, v29
	v_exp_f32_e32 v8, v8
	s_nop 0
	v_add_f32_e32 v8, 1.0, v8
	v_div_scale_f32 v9, s[16:17], v8, v8, v29
	v_rcp_f32_e32 v10, v9
	v_div_scale_f32 v11, vcc, v29, v8, v29
	v_fma_f32 v12, -v9, v10, 1.0
	v_fmac_f32_e32 v10, v12, v10
	v_mul_f32_e32 v12, v11, v10
	v_fma_f32 v13, -v9, v12, v11
	v_fmac_f32_e32 v12, v13, v10
	v_fma_f32 v9, -v9, v12, v11
	v_div_fmas_f32 v9, v9, v10, v12
	v_div_fixup_f32 v4, v9, v8, v29
	ds_write_b32 v7, v4 offset:18432

.LBB0_321:
	s_andn2_b64 vcc, exec, s[0:1]
	s_cbranch_vccnz .LBB0_402
	v_lshlrev_b32_e32 v48, 4, v82
	v_add_u32_e32 v83, 0, v48
	ds_read_b128 v[32:35], v83
	ds_read_b128 v[36:39], v83 offset:1024
	ds_read_b128 v[40:43], v83 offset:2048
	ds_read_b128 v[44:47], v83 offset:3072
	v_lshlrev_b32_e32 v64, 3, v82
	s_cmpk_gt_i32 s26, 0x3ff
	v_mov_b32_e32 v49, v65
	v_lshl_add_u64 v[50:51], s[2:3], 0, v[64:65]
	s_mov_b64 s[2:3], 0x2080000
	s_cselect_b64 s[0:1], -1, 0
	s_add_i32 s22, s26, 0xffffec00
	s_add_i32 s23, s26, 0xfffff800
	s_waitcnt lgkmcnt(0)
	v_lshl_add_u64 v[84:85], s[10:11], 0, v[64:65]
	v_lshl_add_u64 v[86:87], s[14:15], 0, v[48:49]
	v_lshl_add_u64 v[88:89], v[50:51], 0, s[2:3]
	v_lshl_add_u64 v[90:91], s[12:13], 0, v[48:49]
	s_mov_b32 s25, 0
	s_waitcnt vmcnt(0)
	s_branch .LBB0_325

.LBB0_336:
	s_add_i32 s24, s25, 2
	s_cmp_ge_i32 s24, s27
	s_cselect_b64 s[10:11], -1, 0
	s_and_b64 vcc, exec, s[10:11]
	s_nop 0
	v_mov_b32_e32 v51, v19
	v_mov_b32_e32 v50, v18
	v_mov_b32_e32 v49, v17
	v_mov_b32_e32 v48, v16
	v_mov_b32_e32 v55, v23
	v_mov_b32_e32 v54, v22
	v_mov_b32_e32 v53, v21
	v_mov_b32_e32 v52, v20
	v_mov_b32_e32 v59, v27
	v_mov_b32_e32 v58, v26
	v_mov_b32_e32 v57, v25
	v_mov_b32_e32 v56, v24
	v_mov_b32_e32 v63, v31
	v_mov_b32_e32 v62, v30
	v_mov_b32_e32 v61, v29
	v_mov_b32_e32 v60, v28
	s_cbranch_vccnz .LBB0_361
	s_and_b64 vcc, exec, s[2:3]
	s_mov_b64 s[16:17], -1
	s_cbranch_vccnz .LBB0_339
	v_readlane_b32 s13, v254, 14
	s_mul_i32 s13, s24, s13
	s_add_i32 s14, s13, s26
	s_mov_b64 s[16:17], 0

.LBB0_2117:
	s_or_b64 exec, exec, s[26:27]
	v_mul_f32_e32 v19, v1, v1
	v_mul_f32_e32 v20, v3, v3
	v_fmac_f32_e32 v19, v0, v0
	v_fmac_f32_e32 v20, v2, v2
	v_add_f32_e32 v19, v19, v20
	v_mul_f32_e32 v20, v5, v5
	v_mul_f32_e32 v21, v7, v7
	v_fmac_f32_e32 v20, v4, v4
	v_fmac_f32_e32 v21, v6, v6
	v_add_f32_e32 v20, v20, v21
	v_add_f32_e32 v19, v19, v20
	v_mul_f32_e32 v20, v9, v9
	v_mul_f32_e32 v21, v11, v11
	v_fmac_f32_e32 v20, v8, v8
	v_fmac_f32_e32 v21, v10, v10
	v_add_f32_e32 v20, v20, v21
	v_add_f32_e32 v19, v20, v19
	v_mul_f32_e32 v20, v13, v13
	v_mul_f32_e32 v21, v15, v15
	v_fmac_f32_e32 v20, v12, v12
	v_fmac_f32_e32 v21, v14, v14
	v_add_f32_e32 v20, v20, v21
	v_add_f32_e32 v19, v20, v19
	ds_swizzle_b32 v20, v19 offset:swizzle(SWAP,1)
	v_lshlrev_b64 v[16:17], 11, v[16:17]
	v_add_u32_e32 v25, v104, v18
	v_lshl_add_u64 v[26:27], v[92:93], 0, v[16:17]
	s_and_b64 s[12:13], exec, s[12:13]
	s_waitcnt lgkmcnt(0)
	v_add_f32_e32 v19, v19, v20
	ds_swizzle_b32 v20, v19 offset:swizzle(SWAP,2)
	s_or_b64 s[28:29], s[12:13], s[28:29]
	v_lshl_add_u64 v[98:99], v[98:99], 0, s[84:85]
	v_lshl_add_u64 v[100:101], v[100:101], 0, s[52:53]
	v_mov_b32_e32 v96, v97
	s_waitcnt lgkmcnt(0)
	v_add_f32_e32 v19, v19, v20
	ds_swizzle_b32 v20, v19 offset:swizzle(SWAP,4)
	s_waitcnt lgkmcnt(0)
	v_add_f32_e32 v19, v19, v20
	ds_swizzle_b32 v20, v19 offset:swizzle(SWAP,8)
	s_waitcnt lgkmcnt(0)
	v_add_f32_e32 v19, v19, v20
	ds_swizzle_b32 v20, v19 offset:swizzle(SWAP,16)
	s_waitcnt lgkmcnt(0)
	v_add_f32_e32 v19, v19, v20
	v_mov_b32_e32 v20, v19
	s_nop 1
	v_permlane32_swap_b32_e32 v19, v20
	v_add_f32_e32 v19, v19, v20
	v_fmamk_f32 v19, v19, 0x3a800000, v227
	v_cmp_gt_f32_e32 vcc, s74, v19
	v_mul_f32_e32 v20, 0x4b800000, v19
	s_nop 0
	v_cndmask_b32_e32 v19, v19, v20, vcc
	v_rsq_f32_e32 v19, v19
	s_nop 0
	v_mul_f32_e32 v20, 0x45800000, v19
	v_cndmask_b32_e32 v24, v19, v20, vcc
	ds_read_b128 v[16:19], v25 offset:24576
	ds_read_b128 v[20:23], v25 offset:4096
	v_pk_mul_f32 v[2:3], v[2:3], v[24:25] op_sel_hi:[1,0]
	v_pk_mul_f32 v[0:1], v[0:1], v[24:25] op_sel_hi:[1,0]
	v_pk_mul_f32 v[2:3], v[68:69], v[2:3]
	v_pk_mul_f32 v[0:1], v[66:67], v[0:1]
	s_waitcnt lgkmcnt(0)
	v_pk_fma_f32 v[2:3], v[18:19], v[2:3], v[22:23]
	v_pk_fma_f32 v[0:1], v[16:17], v[0:1], v[20:21]
	v_pk_mul_f32 v[6:7], v[6:7], v[24:25] op_sel_hi:[1,0]
	v_cvt_pk_bf16_f32 v0, v0, v1
	v_cvt_pk_bf16_f32 v1, v2, v3
	global_store_dwordx2 v[26:27], v[0:1], off
	ds_read_b128 v[0:3], v25 offset:25600
	ds_read_b128 v[16:19], v25 offset:5120
	v_pk_mul_f32 v[4:5], v[4:5], v[24:25] op_sel_hi:[1,0]
	v_pk_mul_f32 v[6:7], v[72:73], v[6:7]
	v_pk_mul_f32 v[4:5], v[70:71], v[4:5]
	v_pk_mul_f32 v[10:11], v[10:11], v[24:25] op_sel_hi:[1,0]
	s_waitcnt lgkmcnt(0)
	v_pk_fma_f32 v[2:3], v[2:3], v[6:7], v[18:19]
	v_pk_fma_f32 v[0:1], v[0:1], v[4:5], v[16:17]
	v_pk_mul_f32 v[8:9], v[8:9], v[24:25] op_sel_hi:[1,0]
	v_cvt_pk_bf16_f32 v0, v0, v1
	v_cvt_pk_bf16_f32 v1, v2, v3
	global_store_dwordx2 v[26:27], v[0:1], off offset:512
	ds_read_b128 v[0:3], v25 offset:26624
	ds_read_b128 v[4:7], v25 offset:6144
	v_pk_mul_f32 v[8:9], v[74:75], v[8:9]
	v_pk_mul_f32 v[10:11], v[76:77], v[10:11]
	s_waitcnt lgkmcnt(0)
	v_pk_fma_f32 v[0:1], v[0:1], v[8:9], v[4:5]
	v_pk_fma_f32 v[2:3], v[2:3], v[10:11], v[6:7]
	v_cvt_pk_bf16_f32 v0, v0, v1
	v_cvt_pk_bf16_f32 v1, v2, v3
	global_store_dwordx2 v[26:27], v[0:1], off offset:1024
	ds_read_b128 v[0:3], v25 offset:27648
	ds_read_b128 v[4:7], v25 offset:7168
	v_pk_mul_f32 v[8:9], v[14:15], v[24:25] op_sel_hi:[1,0]
	v_pk_mul_f32 v[10:11], v[12:13], v[24:25] op_sel_hi:[1,0]
	v_pk_mul_f32 v[8:9], v[80:81], v[8:9]
	v_pk_mul_f32 v[10:11], v[78:79], v[10:11]
	s_waitcnt lgkmcnt(0)
	v_pk_fma_f32 v[2:3], v[2:3], v[8:9], v[6:7]
	v_pk_fma_f32 v[0:1], v[0:1], v[10:11], v[4:5]
	s_nop 0
	v_cvt_pk_bf16_f32 v0, v0, v1
	v_cvt_pk_bf16_f32 v1, v2, v3
	global_store_dwordx2 v[26:27], v[0:1], off offset:1536
	s_cmp_eq_u32 s100, 0
	s_cbranch_scc1 .Lmy_n2_copyA
	s_cmp_eq_u32 s101, 0
	s_cbranch_scc1 .Lmy_n2_waitA8
	s_waitcnt vmcnt(12)
	s_branch .Lmy_n2_convA
.Lmy_n2_waitA8:
	s_waitcnt vmcnt(8)
.Lmy_n2_convA:
	v_lshlrev_b32_e32 v16, 16, v34
	v_and_b32_e32 v17, 0xffff0000, v34
	v_lshlrev_b32_e32 v18, 16, v35
	v_and_b32_e32 v19, 0xffff0000, v35
	v_lshlrev_b32_e32 v20, 16, v38
	v_and_b32_e32 v21, 0xffff0000, v38
	v_lshlrev_b32_e32 v22, 16, v39
	v_and_b32_e32 v23, 0xffff0000, v39
	v_lshlrev_b32_e32 v24, 16, v42
	v_and_b32_e32 v25, 0xffff0000, v42
	v_lshlrev_b32_e32 v26, 16, v43
	v_and_b32_e32 v27, 0xffff0000, v43
	v_lshlrev_b32_e32 v28, 16, v46
	v_and_b32_e32 v29, 0xffff0000, v46
	v_lshlrev_b32_e32 v30, 16, v47
	v_and_b32_e32 v31, 0xffff0000, v47
	s_branch .Lmy_n2_doB
.Lmy_n2_copyA:
	s_waitcnt vmcnt(4)
	v_mov_b64_e32 v[16:17], v[32:33]
	v_mov_b64_e32 v[18:19], v[34:35]
	v_mov_b64_e32 v[20:21], v[36:37]
	v_mov_b64_e32 v[22:23], v[38:39]
	v_mov_b64_e32 v[24:25], v[40:41]
	v_mov_b64_e32 v[26:27], v[42:43]
	v_mov_b64_e32 v[28:29], v[44:45]
	v_mov_b64_e32 v[30:31], v[46:47]
.Lmy_n2_doB:
	s_cmp_eq_u32 s101, 0
	s_cbranch_scc1 .Lmy_n2_copyB
	s_waitcnt vmcnt(4)
	v_lshlrev_b32_e32 v0, 16, v50
	v_and_b32_e32 v1, 0xffff0000, v50
	v_lshlrev_b32_e32 v2, 16, v51
	v_and_b32_e32 v3, 0xffff0000, v51
	v_lshlrev_b32_e32 v4, 16, v54
	v_and_b32_e32 v5, 0xffff0000, v54
	v_lshlrev_b32_e32 v6, 16, v55
	v_and_b32_e32 v7, 0xffff0000, v55
	v_lshlrev_b32_e32 v8, 16, v58
	v_and_b32_e32 v9, 0xffff0000, v58
	v_lshlrev_b32_e32 v10, 16, v59
	v_and_b32_e32 v11, 0xffff0000, v59
	v_lshlrev_b32_e32 v12, 16, v62
	v_and_b32_e32 v13, 0xffff0000, v62
	v_lshlrev_b32_e32 v14, 16, v63
	v_and_b32_e32 v15, 0xffff0000, v63
	s_branch .Lmy_n2_bottom
.Lmy_n2_copyB:
	s_waitcnt vmcnt(4)
	v_mov_b64_e32 v[0:1], v[48:49]
	v_mov_b64_e32 v[2:3], v[50:51]
	v_mov_b64_e32 v[4:5], v[52:53]
	v_mov_b64_e32 v[6:7], v[54:55]
	v_mov_b64_e32 v[8:9], v[56:57]
	v_mov_b64_e32 v[10:11], v[58:59]
	v_mov_b64_e32 v[12:13], v[60:61]
	v_mov_b64_e32 v[14:15], v[62:63]
.Lmy_n2_bottom:
	s_andn2_b64 exec, exec, s[28:29]
	s_cbranch_execz .LBB0_2141
.LBB0_2118:
	s_mov_b32 s100, 0
	s_mov_b32 s101, 0
	v_cmp_lt_i32_e32 vcc, s65, v96
	s_and_b64 s[26:27], s[72:73], vcc
	s_and_saveexec_b64 s[12:13], s[26:27]
	s_cbranch_execz .LBB0_2120
	v_add_u32_e32 v64, 0xffffc000, v96
	v_lshlrev_b64 v[32:33], 12, v[64:65]
	v_lshl_add_u64 v[32:33], v[90:91], 0, v[32:33]
	s_waitcnt vmcnt(3)
	global_store_dwordx4 v[32:33], v[16:19], off
	s_waitcnt vmcnt(3)
	global_store_dwordx4 v[32:33], v[20:23], off offset:1024
	s_waitcnt vmcnt(3)
	global_store_dwordx4 v[32:33], v[24:27], off offset:2048
	s_waitcnt vmcnt(3)
	global_store_dwordx4 v[32:33], v[28:31], off offset:3072

.LBB0_2124:
	s_andn2_saveexec_b64 s[36:37], s[36:37]
	s_cbranch_execz .LBB0_2126
	s_nop 0
	v_lshl_add_u64 v[44:45], v[100:101], 0, v[84:85]
	global_load_dwordx2 v[34:35], v[44:45], off
	global_load_dwordx2 v[38:39], v[44:45], off offset:512
	global_load_dwordx2 v[42:43], v[44:45], off offset:1024
	global_load_dwordx2 v[46:47], v[44:45], off offset:1536
	s_mov_b32 s100, 1

.LBB0_2135:
.LBB0_2136:
	s_andn2_saveexec_b64 s[36:37], s[36:37]
	s_cbranch_execz .LBB0_2138
	v_ashrrev_i32_e32 v17, 31, v16
	v_lshlrev_b64 v[16:17], 12, v[16:17]
	v_lshl_add_u64 v[16:17], v[88:89], 0, v[16:17]
	global_load_dwordx2 v[50:51], v[16:17], off
	global_load_dwordx2 v[54:55], v[16:17], off offset:512
	global_load_dwordx2 v[58:59], v[16:17], off offset:1024
	global_load_dwordx2 v[62:63], v[16:17], off offset:1536
	s_mov_b32 s101, 1
